# static priority raise for waves 4-7 also in the F1 (RWKV projections/LoRA) item loop
# speedup vs baseline: 1.0080x; 1.0044x over previous
.LBB0_571:
	s_or_b64 exec, exec, s[0:1]
	v_ashrrev_i32_e32 v8, 6, v15
	s_ashr_i32 s0, s66, 4
	v_readlane_b32 s1, v252, 3
	s_waitcnt lgkmcnt(0)
	v_lshl_add_u32 v3, s0, 3, v8
	s_cmp_lt_i32 s0, s1
	s_movk_i32 s1, 0x400
	s_cselect_b64 s[4:5], -1, 0
	v_cmp_gt_i32_e32 vcc, s1, v3
	s_and_b64 s[4:5], s[4:5], vcc
	s_waitcnt vmcnt(0) lgkmcnt(0)
	s_barrier
	s_and_saveexec_b64 s[6:7], s[4:5]
	s_cbranch_execz .LBB0_605
	s_mul_i32 s4, s36, 0xc0000
	s_mov_b32 s5, s73
	s_add_u32 s8, s10, 0xe000000
	s_addc_u32 s9, s11, 0
	s_lshl_b64 s[4:5], s[4:5], 2
	s_add_u32 s1, s10, s4
	s_addc_u32 s4, s11, s5
	s_add_u32 s34, s1, 0x2b100000
	s_addc_u32 s35, s4, 0
	s_add_u32 s38, s10, 0x25000000
	s_addc_u32 s39, s11, 0
	s_add_u32 s1, s10, 0x27000000
	s_addc_u32 s42, s11, 0
	v_bfe_u32 v2, v14, 4, 2
	s_and_b64 s[4:5], s[40:41], exec
	s_movk_i32 s4, 0x3000
	v_lshlrev_b32_e32 v10, 3, v2
	v_lshlrev_b32_e32 v2, 2, v2
	s_cselect_b32 s42, s42, s39
	s_cselect_b32 s1, s1, s38
	v_mul_lo_u32 v0, v8, s4
	v_lshl_or_b32 v2, s37, 6, v2
	s_lshl_b32 s37, s37, 7
	v_add_u32_e32 v11, 0, v0
	v_lshlrev_b32_e32 v0, 4, v14
	s_add_u32 s4, s10, s37
	v_and_b32_e32 v0, 0x70, v0
	s_addc_u32 s5, s11, 0
	v_lshl_add_u64 v[12:13], s[4:5], 0, v[0:1]
	s_mov_b64 s[4:5], 0x1b000000
	v_lshl_add_u64 v[144:145], v[12:13], 0, s[4:5]
	s_mov_b64 s[4:5], 0x1d000000
	v_lshl_add_u64 v[146:147], v[12:13], 0, s[4:5]
	s_mov_b64 s[4:5], 0x1f000000
	v_lshl_add_u64 v[148:149], v[12:13], 0, s[4:5]
	s_add_u32 s4, s1, s37
	s_addc_u32 s5, s42, 0
	v_lshl_add_u64 v[150:151], s[4:5], 0, v[0:1]
	s_mov_b64 s[4:5], 0x29000000
	v_lshl_add_u64 v[164:165], v[12:13], 0, s[4:5]
	s_mov_b64 s[4:5], 0x21000000
	v_lshl_add_u64 v[166:167], v[12:13], 0, s[4:5]
	s_mov_b64 s[4:5], 0x23000000
	v_lshl_add_u64 v[168:169], v[12:13], 0, s[4:5]
	s_add_u32 s4, s8, s37
	s_addc_u32 s5, s9, 0
	v_lshl_add_u64 v[170:171], s[4:5], 0, v[0:1]
	s_mov_b64 s[4:5], 0xe001a00
	v_lshl_add_u64 v[172:173], v[12:13], 0, s[4:5]
	s_mov_b64 s[4:5], 0xe000800
	v_and_b32_e32 v9, 15, v14
	v_lshl_add_u64 v[174:175], v[12:13], 0, s[4:5]
	s_mov_b64 s[4:5], 0xe002200
	s_movk_i32 s1, 0x48
	v_add_u32_e32 v17, v11, v0
	v_lshl_add_u64 v[176:177], v[12:13], 0, s[4:5]
	s_mov_b64 s[4:5], 0xe001000
	v_mad_u32_u24 v0, v9, s1, v10
	v_bfe_u32 v15, v14, 3, 3
	v_lshlrev_b32_e32 v18, 7, v9
	v_lshl_add_u64 v[178:179], v[12:13], 0, s[4:5]
	s_mov_b64 s[4:5], 0xe002a00
	v_lshl_add_u32 v216, v0, 1, 0
	v_and_b32_e32 v0, 48, v14
	v_or_b32_e32 v16, 32, v10
	v_lshl_add_u64 v[180:181], v[12:13], 0, s[4:5]
	v_lshlrev_b32_e32 v12, 7, v15
	v_add_u32_e32 v217, 0, v0
	v_or_b32_e32 v0, v18, v10
	s_lshl_b32 s0, s0, 7
	v_add3_u32 v215, v11, v18, v10
	v_add_u32_e32 v218, v11, v0
	v_lshlrev_b32_e32 v219, 4, v8
	v_or_b32_e32 v220, s0, v15
	v_or_b32_e32 v221, s0, v9
	s_mov_b64 s[42:43], 0
	v_lshlrev_b32_e32 v0, 1, v10
	v_lshlrev_b32_e32 v182, 1, v16
	v_add_u32_e32 v222, v17, v12
	v_readfirstlane_b32 s100, v202
	s_nop 3
	s_lshr_b32 s100, s100, 6
	s_cmp_ge_u32 s100, 4
	s_cbranch_scc0 .Lf1_prio_done
	s_setprio 1
.Lf1_prio_done:
	s_branch .LBB0_574
.LBB0_573:
	v_lshlrev_b32_e32 v90, 16, v12
	v_and_b32_e32 v91, 0xffff0000, v12
	v_lshlrev_b32_e32 v92, 16, v14
	v_and_b32_e32 v93, 0xffff0000, v14
	v_lshlrev_b32_e32 v94, 16, v13
	v_and_b32_e32 v95, 0xffff0000, v13
	v_lshlrev_b32_e32 v12, 16, v15
	v_and_b32_e32 v13, 0xffff0000, v15
	v_lshlrev_b32_e32 v14, 16, v8
	v_and_b32_e32 v15, 0xffff0000, v8
	s_waitcnt lgkmcnt(3)
	v_add_f32_e32 v8, v52, v44
	s_mov_b32 s5, 0xbfb8aa3b
	v_pk_mul_f32 v[62:63], v[102:103], v[66:67]
	v_lshlrev_b32_e32 v102, 16, v10
	v_and_b32_e32 v103, 0xffff0000, v10
	v_mul_f32_e64 v10, |v8|, s5
	v_exp_f32_e32 v10, v10
	v_pk_mul_f32 v[60:61], v[104:105], v[64:65]
	v_lshlrev_b32_e32 v104, 16, v9
	v_and_b32_e32 v105, 0xffff0000, v9
	v_add_f32_e32 v9, 1.0, v10
	s_mov_b32 s4, 0x800000
	v_cmp_gt_f32_e32 vcc, s4, v9
	s_mov_b32 s10, 0x3f317217
	s_mov_b32 s11, 0x7f800000
	v_cndmask_b32_e64 v10, 0, 32, vcc
	v_ldexp_f32 v9, v9, v10
	v_log_f32_e32 v9, v9
	v_max_f32_e64 v8, -v8, 0
	s_waitcnt lgkmcnt(0)
	v_add_f32_e32 v40, v56, v40
	v_mul_f32_e32 v40, 0xbfb8aa3b, v40
	v_mul_f32_e32 v44, 0x3f317217, v9
	v_fma_f32 v44, v9, s10, -v44
	v_fmac_f32_e32 v44, 0x3377d1cf, v9
	v_fmac_f32_e32 v44, 0x3f317217, v9
	v_cmp_lt_f32_e64 s[0:1], |v9|, s11
	v_exp_f32_e32 v40, v40
	v_add_f32_e32 v29, v49, v29
	v_cndmask_b32_e64 v9, v9, v44, s[0:1]
	v_cndmask_b32_e32 v44, 0, v212, vcc
	v_sub_f32_e32 v9, v9, v44
	v_add_f32_e32 v8, v8, v9
	v_sub_f32_e32 v8, -0.5, v8
	v_add_f32_e32 v9, v48, v28
	v_mul_f32_e32 v8, 0x3fb8aa3b, v8
	v_mul_f32_e32 v9, 0xbfb8aa3b, v9
	v_exp_f32_e32 v8, v8
	v_exp_f32_e32 v9, v9
	v_mul_f32_e32 v29, 0xbfb8aa3b, v29
	v_exp_f32_e32 v29, v29
	v_xor_b32_e32 v44, 0x80000000, v8
	v_add_f32_e32 v8, 1.0, v9
	v_add_f32_e32 v9, v53, v45
	v_mul_f32_e64 v28, |v9|, s5
	v_exp_f32_e32 v28, v28
	v_max_f32_e64 v9, -v9, 0
	v_lshlrev_b32_e32 v88, 16, v18
	v_and_b32_e32 v89, 0xffff0000, v18
	v_add_f32_e32 v28, 1.0, v28
	v_cmp_gt_f32_e32 vcc, s4, v28
	v_lshlrev_b32_e32 v86, 16, v16
	v_and_b32_e32 v87, 0xffff0000, v16
	v_cndmask_b32_e64 v45, 0, 32, vcc
	v_ldexp_f32 v28, v28, v45
	v_log_f32_e32 v45, v28
	v_add_f32_e32 v28, 1.0, v40
	v_lshlrev_b32_e32 v106, 16, v11
	v_and_b32_e32 v107, 0xffff0000, v11
	v_mul_f32_e32 v40, 0x3f317217, v45
	v_fma_f32 v40, v45, s10, -v40
	v_fmac_f32_e32 v40, 0x3377d1cf, v45
	v_fmac_f32_e32 v40, 0x3f317217, v45
	v_cmp_lt_f32_e64 s[0:1], |v45|, s11
	v_pk_mul_f32 v[10:11], v[188:189], v[88:89]
	v_rcp_f32_e32 v28, v28
	v_cndmask_b32_e64 v40, v45, v40, s[0:1]
	v_cndmask_b32_e32 v45, 0, v212, vcc
	v_sub_f32_e32 v40, v40, v45
	v_add_f32_e32 v9, v9, v40
	v_add_f32_e32 v40, v57, v41
	v_sub_f32_e32 v9, -0.5, v9
	v_mul_f32_e32 v40, 0xbfb8aa3b, v40
	v_mul_f32_e32 v9, 0x3fb8aa3b, v9
	v_exp_f32_e32 v45, v40
	v_exp_f32_e32 v9, v9
	v_pk_fma_f32 v[40:41], v[190:191], v[86:87], v[10:11]
	v_pk_mul_f32 v[88:89], v[188:189], v[92:93]
	v_add_f32_e32 v10, 1.0, v45
	v_xor_b32_e32 v48, 0x80000000, v9
	v_add_f32_e32 v9, 1.0, v29
	v_rcp_f32_e32 v29, v10
	v_pk_mul_f32 v[92:93], v[188:189], v[102:103]
	v_add_f32_e32 v46, v54, v46
	v_pk_fma_f32 v[10:11], v[190:191], v[14:15], v[92:93]
	v_rcp_f32_e32 v8, v8
	v_pk_add_f32 v[14:15], v[100:101], v[10:11] neg_lo:[0,1] neg_hi:[0,1]
	v_rcp_f32_e32 v9, v9
	v_pk_fma_f32 v[14:15], v[14:15], v[28:29], v[10:11]
	v_add_f32_e32 v42, v58, v42
	v_cndmask_b32_e64 v45, v11, v15, s[40:41]
	v_cndmask_b32_e64 v49, v10, v14, s[40:41]
	v_pk_fma_f32 v[14:15], v[190:191], v[90:91], v[88:89]
	v_pk_add_f32 v[28:29], v[8:9], -1.0 op_sel_hi:[1,0]
	v_pk_mul_f32 v[10:11], v[14:15], v[24:25]
	v_mul_f32_e64 v24, |v46|, s5
	v_exp_f32_e32 v52, v24
	v_pk_fma_f32 v[20:21], v[20:21], v[28:29], 1.0 op_sel_hi:[1,1,0]
	v_mul_f32_e32 v42, 0xbfb8aa3b, v42
	v_pk_mul_f32 v[14:15], v[14:15], v[20:21]
	v_add_f32_e32 v28, 1.0, v52
	v_cmp_gt_f32_e32 vcc, s4, v28
	v_max_f32_e64 v20, -v46, 0
	v_exp_f32_e32 v42, v42
	v_cndmask_b32_e64 v29, 0, 32, vcc
	v_ldexp_f32 v28, v28, v29
	v_log_f32_e32 v28, v28
	v_add_f32_e32 v31, v51, v31
	v_mul_f32_e32 v31, 0xbfb8aa3b, v31
	v_exp_f32_e32 v31, v31
	v_mul_f32_e32 v21, 0x3f317217, v28
	v_fma_f32 v21, v28, s10, -v21
	v_fmac_f32_e32 v21, 0x3377d1cf, v28
	v_fmac_f32_e32 v21, 0x3f317217, v28
	v_cmp_lt_f32_e64 s[0:1], |v28|, s11
	v_lshlrev_b32_e32 v18, 16, v19
	v_and_b32_e32 v19, 0xffff0000, v19
	v_cndmask_b32_e64 v21, v28, v21, s[0:1]
	v_cndmask_b32_e32 v28, 0, v212, vcc
	v_sub_f32_e32 v21, v21, v28
	v_add_f32_e32 v20, v20, v21
	v_sub_f32_e32 v20, -0.5, v20
	v_mul_f32_e32 v20, 0x3fb8aa3b, v20
	v_exp_f32_e32 v46, v20
	v_add_f32_e32 v20, v50, v30
	v_mul_f32_e32 v20, 0xbfb8aa3b, v20
	v_exp_f32_e32 v30, v20
	v_pk_mul_f32 v[20:21], v[188:189], v[12:13]
	v_add_f32_e32 v13, v55, v47
	v_lshlrev_b32_e32 v16, 16, v17
	v_add_f32_e32 v12, 1.0, v30
	v_mul_f32_e64 v30, |v13|, s5
	v_exp_f32_e32 v30, v30
	v_max_f32_e64 v13, -v13, 0
	v_and_b32_e32 v17, 0xffff0000, v17
	v_pk_mul_f32 v[18:19], v[188:189], v[18:19]
	v_add_f32_e32 v30, 1.0, v30
	v_cmp_gt_f32_e32 vcc, s4, v30
	v_pk_fma_f32 v[16:17], v[190:191], v[16:17], v[18:19]
	v_pk_mul_f32 v[28:29], v[188:189], v[106:107]
	v_cndmask_b32_e64 v47, 0, 32, vcc
	v_ldexp_f32 v30, v30, v47
	v_log_f32_e32 v47, v30
	v_add_f32_e32 v30, 1.0, v42
	v_rcp_f32_e32 v30, v30
	v_rcp_f32_e32 v12, v12
	v_mul_f32_e32 v42, 0x3f317217, v47
	v_fma_f32 v42, v47, s10, -v42
	v_fmac_f32_e32 v42, 0x3377d1cf, v47
	v_fmac_f32_e32 v42, 0x3f317217, v47
	v_cmp_lt_f32_e64 s[0:1], |v47|, s11
	v_xor_b32_e32 v46, 0x80000000, v46
	v_cvt_pk_bf16_f32 v14, v14, v15
	v_cndmask_b32_e64 v42, v47, v42, s[0:1]
	v_cndmask_b32_e32 v47, 0, v212, vcc
	v_sub_f32_e32 v42, v42, v47
	v_add_f32_e32 v13, v13, v42
	v_add_f32_e32 v42, v59, v43
	v_sub_f32_e32 v13, -0.5, v13
	v_mul_f32_e32 v42, 0xbfb8aa3b, v42
	v_mul_f32_e32 v13, 0x3fb8aa3b, v13
	v_exp_f32_e32 v42, v42
	v_exp_f32_e32 v13, v13
	v_ashrrev_i32_e32 v187, 31, v186
	v_ashrrev_i32_e32 v185, 31, v184
	v_add_f32_e32 v18, 1.0, v42
	v_xor_b32_e32 v43, 0x80000000, v13
	v_add_f32_e32 v13, 1.0, v31
	v_rcp_f32_e32 v31, v18
	v_rcp_f32_e32 v13, v13
	v_pk_fma_f32 v[18:19], v[190:191], v[104:105], v[28:29]
	v_pk_mul_f32 v[72:73], v[120:121], v[72:73]
	v_pk_add_f32 v[28:29], v[84:85], v[18:19] neg_lo:[0,1] neg_hi:[0,1]
	v_pk_mul_f32 v[76:77], v[72:73], v[72:73]
	v_pk_fma_f32 v[28:29], v[28:29], v[30:31], v[18:19]
	v_pk_mul_f32 v[74:75], v[122:123], v[74:75]
	v_cndmask_b32_e64 v30, v19, v29, s[40:41]
	v_cndmask_b32_e64 v31, v18, v28, s[40:41]
	v_pk_fma_f32 v[18:19], v[190:191], v[94:95], v[20:21]
	v_pk_add_f32 v[20:21], v[12:13], -1.0 op_sel_hi:[1,0]
	v_pk_mul_f32 v[26:27], v[18:19], v[26:27]
	v_pk_fma_f32 v[20:21], v[22:23], v[20:21], 1.0 op_sel_hi:[1,1,0]
	v_add_u32_e32 v22, 0x60, v218
	v_pk_mul_f32 v[18:19], v[18:19], v[20:21]
	v_cvt_pk_bf16_f32 v20, v40, v41
	v_cvt_pk_bf16_f32 v21, v16, v17
	v_cvt_pk_bf16_f32 v16, v44, v48
	v_cvt_pk_bf16_f32 v17, v46, v43
	ds_write2st64_b64 v22, v[20:21], v[16:17] offset0:75 offset1:79
	v_cvt_pk_bf16_f32 v15, v18, v19
	v_cvt_pk_bf16_f32 v16, v49, v45
	v_cvt_pk_bf16_f32 v17, v31, v30
	ds_write2st64_b64 v22, v[14:15], v[16:17] offset0:83 offset1:87
	v_cvt_pk_bf16_f32 v14, v36, v37
	v_cvt_pk_bf16_f32 v15, v38, v39
	ds_write_b64 v218, v[14:15] offset:46688
	s_waitcnt lgkmcnt(0)
	ds_read_b128 v[14:17], v222 offset:38400
	ds_read_b128 v[18:21], v222 offset:39424
	v_lshlrev_b64 v[22:23], 11, v[186:187]
	v_lshl_add_u64 v[30:31], v[144:145], 0, v[22:23]
	v_pk_mul_f32 v[78:79], v[74:75], v[74:75]
	s_waitcnt lgkmcnt(1)
	global_store_dwordx4 v[30:31], v[14:17], off
	ds_read_b128 v[14:17], v222 offset:40448
	v_lshlrev_b64 v[30:31], 11, v[184:185]
	v_lshl_add_u64 v[36:37], v[144:145], 0, v[30:31]
	s_waitcnt lgkmcnt(1)
	global_store_dwordx4 v[36:37], v[18:21], off
	ds_read_b128 v[18:21], v222 offset:41472
	v_lshl_add_u64 v[36:37], v[146:147], 0, v[22:23]
	s_waitcnt lgkmcnt(1)
	global_store_dwordx4 v[36:37], v[14:17], off
	ds_read_b128 v[14:17], v222 offset:42496
	v_lshl_add_u64 v[36:37], v[146:147], 0, v[30:31]
	s_waitcnt lgkmcnt(1)
	global_store_dwordx4 v[36:37], v[18:21], off
	v_lshl_add_u64 v[36:37], v[148:149], 0, v[22:23]
	ds_read_b128 v[18:21], v222 offset:43520
	s_waitcnt lgkmcnt(1)
	global_store_dwordx4 v[36:37], v[14:17], off
	v_pk_mul_f32 v[64:65], v[60:61], v[60:61]
	v_pk_mul_f32 v[66:67], v[62:63], v[62:63]
	v_add_f32_e32 v16, v76, v77
	v_add_f32_e32 v16, v78, v16
	v_add_f32_e32 v16, v79, v16
	v_add_f32_e32 v16, v16, v64
	v_add_f32_e32 v16, v65, v16
	v_pk_mul_f32 v[32:33], v[80:81], v[32:33]
	v_add_f32_e32 v16, v66, v16
	v_pk_mul_f32 v[80:81], v[32:33], v[32:33]
	v_add_f32_e32 v16, v67, v16
	v_pk_mul_f32 v[34:35], v[82:83], v[34:35]
	v_add_f32_e32 v16, v16, v80
	v_pk_mul_f32 v[82:83], v[34:35], v[34:35]
	v_add_f32_e32 v16, v81, v16
	v_add_f32_e32 v16, v82, v16
	v_pk_mul_f32 v[24:25], v[10:11], v[10:11]
	v_add_f32_e32 v16, v83, v16
	v_add_f32_e32 v16, v16, v24
	v_pk_mul_f32 v[28:29], v[26:27], v[26:27]
	v_add_f32_e32 v16, v25, v16
	v_add_f32_e32 v16, v28, v16
	v_cmp_lt_i32_e32 vcc, v209, v210
	v_add_f32_e32 v28, v29, v16
	v_lshl_add_u64 v[14:15], v[148:149], 0, v[30:31]
	v_cndmask_b32_e32 v16, v208, v209, vcc
	v_lshlrev_b32_e32 v16, 2, v16
	ds_bpermute_b32 v29, v16, v28
	v_cmp_lt_i32_e32 vcc, v211, v210
	s_waitcnt lgkmcnt(1)
	global_store_dwordx4 v[14:15], v[18:21], off
	ds_read_b128 v[14:17], v222 offset:44544
	ds_read_b128 v[18:21], v222 offset:45568
	v_lshl_add_u64 v[24:25], v[150:151], 0, v[22:23]
	s_waitcnt lgkmcnt(2)
	v_add_f32_e32 v28, v28, v29
	v_cndmask_b32_e32 v29, v208, v211, vcc
	v_lshlrev_b32_e32 v29, 2, v29
	ds_bpermute_b32 v29, v29, v28
	s_waitcnt lgkmcnt(2)
	global_store_dwordx4 v[24:25], v[14:17], off
	s_mov_b32 s0, 0xf800000
	v_lshl_add_u64 v[24:25], v[164:165], 0, v[22:23]
	v_lshl_add_u64 v[14:15], v[150:151], 0, v[30:31]
	s_waitcnt lgkmcnt(1)
	global_store_dwordx4 v[14:15], v[18:21], off
	ds_read_b128 v[14:17], v222 offset:46592
	s_waitcnt lgkmcnt(1)
	v_add_f32_e32 v18, v28, v29
	v_mul_f32_e32 v19, 0x4f800000, v18
	v_cmp_gt_f32_e32 vcc, s0, v18
	s_nop 1
	v_cndmask_b32_e32 v28, v18, v19, vcc
	v_sqrt_f32_e32 v29, v28
	ds_read_b128 v[18:21], v222 offset:47616
	s_waitcnt lgkmcnt(1)
	global_store_dwordx4 v[24:25], v[14:17], off
	s_nop 1
	v_add_u32_e32 v14, -1, v29
	v_fma_f32 v15, -v14, v29, v28
	v_cmp_ge_f32_e64 s[0:1], 0, v15
	v_add_u32_e32 v15, 1, v29
	v_fma_f32 v16, -v15, v29, v28
	v_cndmask_b32_e64 v14, v29, v14, s[0:1]
	v_cmp_lt_f32_e64 s[0:1], 0, v16
	s_nop 1
	v_cndmask_b32_e64 v14, v14, v15, s[0:1]
	v_mul_f32_e32 v15, 0x37800000, v14
	v_cndmask_b32_e32 v14, v14, v15, vcc
	v_cmp_class_f32_e32 vcc, v28, v207
	s_nop 1
	v_cndmask_b32_e32 v14, v14, v28, vcc
	v_max_f32_e32 v16, 0x2b8cbccc, v14
	v_div_scale_f32 v17, s[0:1], v16, v16, 1.0
	v_rcp_f32_e32 v24, v17
	v_lshl_add_u64 v[14:15], v[164:165], 0, v[30:31]
	s_waitcnt lgkmcnt(0)
	global_store_dwordx4 v[14:15], v[18:21], off
	s_waitcnt lgkmcnt(0)
	v_fma_f32 v14, -v17, v24, 1.0
	v_fmac_f32_e32 v24, v14, v24
	v_div_scale_f32 v14, vcc, 1.0, v16, 1.0
	v_mul_f32_e32 v15, v14, v24
	v_fma_f32 v18, -v17, v15, v14
	v_fmac_f32_e32 v15, v18, v24
	v_fma_f32 v14, -v17, v15, v14
	v_div_fmas_f32 v14, v14, v24, v15
	v_div_fixup_f32 v14, v14, v16, 1.0
	v_pk_mul_f32 v[16:17], v[72:73], v[14:15] op_sel_hi:[1,0]
	v_pk_mul_f32 v[20:21], v[74:75], v[14:15] op_sel_hi:[1,0]
	v_pk_mul_f32 v[18:19], v[116:117], v[16:17]
	v_pk_mul_f32 v[24:25], v[118:119], v[20:21]
	v_pk_add_f32 v[16:17], v[16:17], 0 neg_lo:[1,1] neg_hi:[1,1]
	v_pk_add_f32 v[20:21], v[20:21], 0 neg_lo:[1,1] neg_hi:[1,1]
	v_cvt_pk_bf16_f32 v16, v16, v17
	v_cvt_pk_bf16_f32 v17, v20, v21
	v_pk_mul_f32 v[20:21], v[60:61], v[14:15] op_sel_hi:[1,0]
	v_pk_mul_f32 v[28:29], v[62:63], v[14:15] op_sel_hi:[1,0]
	v_cvt_pk_bf16_f32 v18, v18, v19
	v_cvt_pk_bf16_f32 v19, v24, v25
	v_pk_mul_f32 v[24:25], v[96:97], v[20:21]
	v_pk_mul_f32 v[36:37], v[98:99], v[28:29]
	v_pk_add_f32 v[20:21], v[20:21], 0 neg_lo:[1,1] neg_hi:[1,1]
	v_pk_add_f32 v[28:29], v[28:29], 0 neg_lo:[1,1] neg_hi:[1,1]
	v_cvt_pk_bf16_f32 v20, v20, v21
	v_cvt_pk_bf16_f32 v21, v28, v29
	v_add_u32_e32 v28, 0x9000, v218
	ds_write2_b64 v28, v[16:17], v[20:21] offset0:192 offset1:196
	v_cvt_pk_bf16_f32 v16, v24, v25
	v_cvt_pk_bf16_f32 v17, v36, v37
	v_add_u32_e32 v29, 0x9800, v218
	ds_write2_b64 v29, v[18:19], v[16:17] offset0:192 offset1:196
	v_pk_mul_f32 v[16:17], v[32:33], v[14:15] op_sel_hi:[1,0]
	v_pk_mul_f32 v[20:21], v[34:35], v[14:15] op_sel_hi:[1,0]
	v_pk_mul_f32 v[10:11], v[10:11], v[14:15] op_sel_hi:[1,0]
	v_pk_mul_f32 v[14:15], v[26:27], v[14:15] op_sel_hi:[1,0]
	v_pk_mul_f32 v[18:19], v[68:69], v[16:17]
	v_pk_mul_f32 v[24:25], v[70:71], v[20:21]
	v_pk_add_f32 v[16:17], v[16:17], 0 neg_lo:[1,1] neg_hi:[1,1]
	v_pk_add_f32 v[20:21], v[20:21], 0 neg_lo:[1,1] neg_hi:[1,1]
	v_pk_mul_f32 v[8:9], v[8:9], v[10:11]
	v_pk_mul_f32 v[12:13], v[12:13], v[14:15]
	v_pk_add_f32 v[10:11], v[10:11], 0 neg_lo:[1,1] neg_hi:[1,1]
	v_pk_add_f32 v[14:15], v[14:15], 0 neg_lo:[1,1] neg_hi:[1,1]
	v_cvt_pk_bf16_f32 v16, v16, v17
	v_cvt_pk_bf16_f32 v17, v20, v21
	v_cvt_pk_bf16_f32 v18, v18, v19
	v_cvt_pk_bf16_f32 v19, v24, v25
	v_cvt_pk_bf16_f32 v10, v10, v11
	v_cvt_pk_bf16_f32 v11, v14, v15
	v_cvt_pk_bf16_f32 v8, v8, v9
	v_cvt_pk_bf16_f32 v9, v12, v13
	ds_write2_b64 v28, v[16:17], v[10:11] offset0:200 offset1:204
	ds_write2_b64 v29, v[18:19], v[8:9] offset0:200 offset1:204
	s_waitcnt lgkmcnt(0)
	ds_read_b128 v[8:11], v222 offset:38400
	ds_read_b128 v[12:15], v222 offset:39424
	v_lshl_add_u64 v[16:17], v[166:167], 0, v[22:23]
	v_lshl_add_u64 v[20:21], v[166:167], 0, v[30:31]
	v_readlane_b32 s0, v251, 54
	s_waitcnt lgkmcnt(1)
	global_store_dwordx4 v[16:17], v[8:11], off
	ds_read_b128 v[8:11], v222 offset:40448
	ds_read_b128 v[16:19], v222 offset:41472
	s_waitcnt lgkmcnt(2)
	global_store_dwordx4 v[20:21], v[12:15], off
	v_add_u32_e32 v3, s0, v3
	s_movk_i32 s0, 0x3ff
	v_lshl_add_u64 v[12:13], v[168:169], 0, v[22:23]
	s_waitcnt lgkmcnt(1)
	global_store_dwordx4 v[12:13], v[8:11], off
	v_readlane_b32 s1, v252, 4
	v_cmp_lt_i32_e32 vcc, s0, v3
	v_lshl_add_u64 v[8:9], v[168:169], 0, v[30:31]
	s_waitcnt lgkmcnt(0)
	global_store_dwordx4 v[8:9], v[16:19], off
	s_waitcnt lgkmcnt(0)
	v_add_u32_e32 v220, s1, v220
	s_or_b64 s[42:43], vcc, s[42:43]
	v_add_u32_e32 v221, s1, v221
	s_andn2_b64 exec, exec, s[42:43]
	s_cbranch_execz .LBB0_605

.LBB0_605:
	s_setprio 0
	s_or_b64 exec, exec, s[6:7]
	s_mov_b64 s[0:1], 0
